# P5 epilogue: per-row ss values prefetched one tile ahead into spare registers (no load wait at the epilogue top)
# speedup vs baseline: 1.0013x; 1.0013x over previous
.LBB0_1043:
	s_lshl_b32 s1, s10, 5
	s_mov_b64 s[10:11], 0x80
	s_and_b32 s16, s1, 0x60
	s_add_i32 m0, s31, 0x18000
	v_lshl_add_u64 v[6:7], v[6:7], 0, s[10:11]
	s_lshl_b32 s13, s12, 13
	s_lshl_b32 s17, s16, 7
	s_waitcnt vmcnt(2)
	s_barrier
	global_load_lds_dwordx4 v[6:7], off
	v_lshl_add_u64 v[4:5], v[4:5], 0, s[10:11]
	s_add_i32 m0, s31, 0x1a000
	s_add_i32 s37, s31, 0x8000
	s_add_i32 s38, s31, 0xa000
	global_load_lds_dwordx4 v[4:5], off
	v_lshl_add_u64 v[0:1], v[0:1], 0, s[10:11]
	s_mov_b32 m0, s37
	s_add_u32 s14, s2, 0x40080
	global_load_lds_dwordx4 v[0:1], off
	v_lshl_add_u64 v[0:1], v[2:3], 0, s[10:11]
	s_mov_b32 m0, s38
	s_addc_u32 s15, s3, 0
	global_load_lds_dwordx4 v[0:1], off
	s_add_i32 m0, s31, 0x1c000
	v_lshl_add_u64 v[0:1], s[14:15], 0, v[132:133]
	global_load_lds_dwordx4 v[0:1], off
	v_lshl_add_u64 v[0:1], s[14:15], 0, v[128:129]
	s_add_i32 m0, s31, 0x1e000
	s_cmpk_lt_u32 s5, 0x100
	global_load_lds_dwordx4 v[0:1], off
	v_lshrrev_b32_e32 v1, 1, v9
	v_and_b32_e32 v1, 24, v1
	v_and_b32_e32 v0, 15, v9
	v_lshlrev_b32_e32 v2, 1, v1
	v_lshl_or_b32 v148, s12, 6, v0
	v_lshl_or_b32 v0, v0, 6, v2
	v_lshlrev_b32_e32 v2, 2, v9
	v_and_b32_e32 v2, 32, v2
	v_bitop3_b32 v3, v0, s13, v2 bitop3:0xde
	v_bitop3_b32 v149, v0, s17, v2 bitop3:0xde
	v_lshlrev_b32_e32 v0, 14, v13
	v_and_b32_e32 v0, 0xffff8000, v0
	v_or_b32_e32 v150, s16, v1
	v_lshl_add_u32 v0, v12, 11, v0
	v_and_b32_e32 v1, 1, v13
	v_lshl_or_b32 v0, v1, 6, v0
	v_lshl_add_u32 v136, v14, 1, v0
	v_lshlrev_b32_e32 v0, 14, v8
	v_and_b32_e32 v0, 0xffff8000, v0
	s_waitcnt vmcnt(6)
	v_lshl_add_u32 v0, v10, 11, v0
	v_and_b32_e32 v1, 1, v8
	s_cselect_b64 s[12:13], -1, 0
	v_lshl_or_b32 v0, v1, 6, v0
	s_add_i32 s41, 0, 0x10000
	s_add_i32 s42, 0, 0x14000
	s_sext_i32_i16 s1, s4
	s_ashr_i32 s39, s86, 31
	s_mov_b32 s40, s86
	v_mov_b32_e32 v137, v133
	v_lshl_add_u32 v138, v11, 1, v0
	v_mov_b32_e32 v139, v133
	v_mov_b64_e32 v[140:141], 0xb00
	v_mov_b64_e32 v[142:143], 0xaff
	v_add_u32_e32 v151, s41, v149
	v_add_u32_e32 v152, s42, v149
	v_add_u32_e32 v153, 0, v3
	v_mov_b32_e32 v154, 0x358637bd
	s_mov_b32 s43, 0x800000
	s_movk_i32 s44, 0x1600
	s_barrier
	v_lshl_add_u32 v146, s0, 8, v148
	v_ashrrev_i32_e32 v147, 31, v146
	v_lshl_add_u64 v[146:147], v[146:147], 2, s[54:55]
	global_load_dword v228, v[146:147], off
	global_load_dword v229, v[146:147], off offset:64
	global_load_dword v230, v[146:147], off offset:128
	global_load_dword v231, v[146:147], off offset:192
	global_load_dword v232, v[146:147], off offset:512
	global_load_dword v233, v[146:147], off offset:576
	global_load_dword v234, v[146:147], off offset:640
	global_load_dword v235, v[146:147], off offset:704
	s_branch .LBB0_1046

.LBB0_1052:
	v_lshl_add_u32 v144, s0, 8, v148
	v_lshl_or_b32 v156, s1, 7, v150
	v_readlane_b32 s0, v246, 26
	v_readlane_b32 s1, v246, 27
	v_mov_b32_e32 v157, 0
	s_mov_b32 s2, 0x16000
	s_mov_b32 s3, 0
	v_mov_b64_e32 v[158:159], s[0:1]
	v_mad_i64_i32 v[160:161], vcc, v144, s44, v[158:159]
	s_mov_b32 s0, 0xbfb8aa3b
	v_lshl_add_u64 v[156:157], v[156:157], 1, v[160:161]
	s_mov_b32 vcc_lo, 0xb0000
	s_mov_b32 vcc_hi, 0
	v_lshl_add_u64 v[158:159], v[156:157], 0, s[2:3]
	v_lshl_add_u64 v[164:165], v[156:157], 0, vcc
	v_lshl_add_u64 v[160:161], v[158:159], 0, s[2:3]
	v_lshl_add_u64 v[166:167], v[164:165], 0, s[2:3]
	v_lshl_add_u64 v[162:163], v[160:161], 0, s[2:3]
	v_lshl_add_u64 v[168:169], v[166:167], 0, s[2:3]
	v_lshl_add_u64 v[170:171], v[168:169], 0, s[2:3]
	v_fmamk_f32 v188, v228, 0x3a800000, v154
	v_fmamk_f32 v190, v229, 0x3a800000, v154
	v_fmamk_f32 v192, v230, 0x3a800000, v154
	v_fmamk_f32 v194, v231, 0x3a800000, v154
	v_fmamk_f32 v196, v232, 0x3a800000, v154
	v_fmamk_f32 v198, v233, 0x3a800000, v154
	v_fmamk_f32 v200, v234, 0x3a800000, v154
	v_fmamk_f32 v202, v235, 0x3a800000, v154
	s_and_b64 vcc, exec, s[4:5]
	s_cbranch_vccz .Lp5h_nonext
	v_lshl_add_u32 v146, s16, 8, v148
	v_ashrrev_i32_e32 v147, 31, v146
	v_lshl_add_u64 v[146:147], v[146:147], 2, s[54:55]
	global_load_dword v228, v[146:147], off
	global_load_dword v229, v[146:147], off offset:64
	global_load_dword v230, v[146:147], off offset:128
	global_load_dword v231, v[146:147], off offset:192
	global_load_dword v232, v[146:147], off offset:512
	global_load_dword v233, v[146:147], off offset:576
	global_load_dword v234, v[146:147], off offset:640
	global_load_dword v235, v[146:147], off offset:704
.Lp5h_nonext:
	v_rsq_f32_e32 v188, v188
	v_rsq_f32_e32 v190, v190
	v_rsq_f32_e32 v192, v192
	v_rsq_f32_e32 v194, v194
	v_rsq_f32_e32 v196, v196
	v_rsq_f32_e32 v198, v198
	v_rsq_f32_e32 v200, v200
	v_rsq_f32_e32 v202, v202
	v_pk_mul_f32 v[116:117], v[116:117], v[188:189] op_sel_hi:[1,0]
	v_pk_mul_f32 v[118:119], v[118:119], v[188:189] op_sel_hi:[1,0]
	v_pk_mul_f32 v[112:113], v[112:113], v[188:189] op_sel_hi:[1,0]
	v_pk_mul_f32 v[114:115], v[114:115], v[188:189] op_sel_hi:[1,0]
	v_pk_mul_f32 v[124:125], v[124:125], v[188:189] op_sel_hi:[1,0]
	v_pk_mul_f32 v[126:127], v[126:127], v[188:189] op_sel_hi:[1,0]
	v_pk_mul_f32 v[120:121], v[120:121], v[188:189] op_sel_hi:[1,0]
	v_pk_mul_f32 v[122:123], v[122:123], v[188:189] op_sel_hi:[1,0]
	v_pk_mul_f32 v[172:173], v[116:117], s[0:1] op_sel_hi:[1,0]
	v_pk_mul_f32 v[174:175], v[118:119], s[0:1] op_sel_hi:[1,0]
	v_pk_mul_f32 v[176:177], v[112:113], s[0:1] op_sel_hi:[1,0]
	v_pk_mul_f32 v[178:179], v[114:115], s[0:1] op_sel_hi:[1,0]
	v_exp_f32_e32 v172, v172
	v_exp_f32_e32 v173, v173
	v_exp_f32_e32 v174, v174
	v_exp_f32_e32 v175, v175
	v_exp_f32_e32 v176, v176
	v_exp_f32_e32 v177, v177
	v_exp_f32_e32 v178, v178
	v_exp_f32_e32 v179, v179
	v_pk_add_f32 v[172:173], v[172:173], 1.0 op_sel_hi:[1,0]
	v_pk_add_f32 v[174:175], v[174:175], 1.0 op_sel_hi:[1,0]
	v_pk_add_f32 v[176:177], v[176:177], 1.0 op_sel_hi:[1,0]
	v_pk_add_f32 v[178:179], v[178:179], 1.0 op_sel_hi:[1,0]
	v_rcp_f32_e32 v172, v172
	v_rcp_f32_e32 v173, v173
	v_rcp_f32_e32 v174, v174
	v_rcp_f32_e32 v175, v175
	v_rcp_f32_e32 v176, v176
	v_rcp_f32_e32 v177, v177
	v_rcp_f32_e32 v178, v178
	v_rcp_f32_e32 v179, v179
	v_pk_mul_f32 v[172:173], v[116:117], v[172:173]
	v_pk_mul_f32 v[174:175], v[118:119], v[174:175]
	v_pk_mul_f32 v[176:177], v[112:113], v[176:177]
	v_pk_mul_f32 v[178:179], v[114:115], v[178:179]
	v_pk_mul_f32 v[124:125], v[124:125], v[172:173]
	v_pk_mul_f32 v[126:127], v[126:127], v[174:175]
	v_pk_mul_f32 v[120:121], v[120:121], v[176:177]
	v_pk_mul_f32 v[122:123], v[122:123], v[178:179]
	v_cvt_pk_bf16_f32 v116, v124, v125
	v_cvt_pk_bf16_f32 v117, v126, v127
	v_cvt_pk_bf16_f32 v118, v120, v121
	v_cvt_pk_bf16_f32 v119, v122, v123
	global_store_dwordx4 v[156:157], v[116:119], off nt
	v_pk_mul_f32 v[100:101], v[100:101], v[190:191] op_sel_hi:[1,0]
	v_pk_mul_f32 v[102:103], v[102:103], v[190:191] op_sel_hi:[1,0]
	v_pk_mul_f32 v[96:97], v[96:97], v[190:191] op_sel_hi:[1,0]
	v_pk_mul_f32 v[98:99], v[98:99], v[190:191] op_sel_hi:[1,0]
	v_pk_mul_f32 v[108:109], v[108:109], v[190:191] op_sel_hi:[1,0]
	v_pk_mul_f32 v[110:111], v[110:111], v[190:191] op_sel_hi:[1,0]
	v_pk_mul_f32 v[104:105], v[104:105], v[190:191] op_sel_hi:[1,0]
	v_pk_mul_f32 v[106:107], v[106:107], v[190:191] op_sel_hi:[1,0]
	v_pk_mul_f32 v[180:181], v[100:101], s[0:1] op_sel_hi:[1,0]
	v_pk_mul_f32 v[182:183], v[102:103], s[0:1] op_sel_hi:[1,0]
	v_pk_mul_f32 v[184:185], v[96:97], s[0:1] op_sel_hi:[1,0]
	v_pk_mul_f32 v[186:187], v[98:99], s[0:1] op_sel_hi:[1,0]
	v_exp_f32_e32 v180, v180
	v_exp_f32_e32 v181, v181
	v_exp_f32_e32 v182, v182
	v_exp_f32_e32 v183, v183
	v_exp_f32_e32 v184, v184
	v_exp_f32_e32 v185, v185
	v_exp_f32_e32 v186, v186
	v_exp_f32_e32 v187, v187
	v_pk_add_f32 v[180:181], v[180:181], 1.0 op_sel_hi:[1,0]
	v_pk_add_f32 v[182:183], v[182:183], 1.0 op_sel_hi:[1,0]
	v_pk_add_f32 v[184:185], v[184:185], 1.0 op_sel_hi:[1,0]
	v_pk_add_f32 v[186:187], v[186:187], 1.0 op_sel_hi:[1,0]
	v_rcp_f32_e32 v180, v180
	v_rcp_f32_e32 v181, v181
	v_rcp_f32_e32 v182, v182
	v_rcp_f32_e32 v183, v183
	v_rcp_f32_e32 v184, v184
	v_rcp_f32_e32 v185, v185
	v_rcp_f32_e32 v186, v186
	v_rcp_f32_e32 v187, v187
	v_pk_mul_f32 v[180:181], v[100:101], v[180:181]
	v_pk_mul_f32 v[182:183], v[102:103], v[182:183]
	v_pk_mul_f32 v[184:185], v[96:97], v[184:185]
	v_pk_mul_f32 v[186:187], v[98:99], v[186:187]
	v_pk_mul_f32 v[108:109], v[108:109], v[180:181]
	v_pk_mul_f32 v[110:111], v[110:111], v[182:183]
	v_pk_mul_f32 v[104:105], v[104:105], v[184:185]
	v_pk_mul_f32 v[106:107], v[106:107], v[186:187]
	v_cvt_pk_bf16_f32 v100, v108, v109
	v_cvt_pk_bf16_f32 v101, v110, v111
	v_cvt_pk_bf16_f32 v102, v104, v105
	v_cvt_pk_bf16_f32 v103, v106, v107
	global_store_dwordx4 v[158:159], v[100:103], off nt
	v_pk_mul_f32 v[84:85], v[84:85], v[192:193] op_sel_hi:[1,0]
	v_pk_mul_f32 v[86:87], v[86:87], v[192:193] op_sel_hi:[1,0]
	v_pk_mul_f32 v[80:81], v[80:81], v[192:193] op_sel_hi:[1,0]
	v_pk_mul_f32 v[82:83], v[82:83], v[192:193] op_sel_hi:[1,0]
	v_pk_mul_f32 v[92:93], v[92:93], v[192:193] op_sel_hi:[1,0]
	v_pk_mul_f32 v[94:95], v[94:95], v[192:193] op_sel_hi:[1,0]
	v_pk_mul_f32 v[88:89], v[88:89], v[192:193] op_sel_hi:[1,0]
	v_pk_mul_f32 v[90:91], v[90:91], v[192:193] op_sel_hi:[1,0]
	v_pk_mul_f32 v[172:173], v[84:85], s[0:1] op_sel_hi:[1,0]
	v_pk_mul_f32 v[174:175], v[86:87], s[0:1] op_sel_hi:[1,0]
	v_pk_mul_f32 v[176:177], v[80:81], s[0:1] op_sel_hi:[1,0]
	v_pk_mul_f32 v[178:179], v[82:83], s[0:1] op_sel_hi:[1,0]
	v_exp_f32_e32 v172, v172
	v_exp_f32_e32 v173, v173
	v_exp_f32_e32 v174, v174
	v_exp_f32_e32 v175, v175
	v_exp_f32_e32 v176, v176
	v_exp_f32_e32 v177, v177
	v_exp_f32_e32 v178, v178
	v_exp_f32_e32 v179, v179
	v_pk_add_f32 v[172:173], v[172:173], 1.0 op_sel_hi:[1,0]
	v_pk_add_f32 v[174:175], v[174:175], 1.0 op_sel_hi:[1,0]
	v_pk_add_f32 v[176:177], v[176:177], 1.0 op_sel_hi:[1,0]
	v_pk_add_f32 v[178:179], v[178:179], 1.0 op_sel_hi:[1,0]
	v_rcp_f32_e32 v172, v172
	v_rcp_f32_e32 v173, v173
	v_rcp_f32_e32 v174, v174
	v_rcp_f32_e32 v175, v175
	v_rcp_f32_e32 v176, v176
	v_rcp_f32_e32 v177, v177
	v_rcp_f32_e32 v178, v178
	v_rcp_f32_e32 v179, v179
	v_pk_mul_f32 v[172:173], v[84:85], v[172:173]
	v_pk_mul_f32 v[174:175], v[86:87], v[174:175]
	v_pk_mul_f32 v[176:177], v[80:81], v[176:177]
	v_pk_mul_f32 v[178:179], v[82:83], v[178:179]
	v_pk_mul_f32 v[92:93], v[92:93], v[172:173]
	v_pk_mul_f32 v[94:95], v[94:95], v[174:175]
	v_pk_mul_f32 v[88:89], v[88:89], v[176:177]
	v_pk_mul_f32 v[90:91], v[90:91], v[178:179]
	v_cvt_pk_bf16_f32 v84, v92, v93
	v_cvt_pk_bf16_f32 v85, v94, v95
	v_cvt_pk_bf16_f32 v86, v88, v89
	v_cvt_pk_bf16_f32 v87, v90, v91
	global_store_dwordx4 v[160:161], v[84:87], off nt
	v_pk_mul_f32 v[72:73], v[72:73], v[194:195] op_sel_hi:[1,0]
	v_pk_mul_f32 v[74:75], v[74:75], v[194:195] op_sel_hi:[1,0]
	v_pk_mul_f32 v[64:65], v[64:65], v[194:195] op_sel_hi:[1,0]
	v_pk_mul_f32 v[66:67], v[66:67], v[194:195] op_sel_hi:[1,0]
	v_pk_mul_f32 v[76:77], v[76:77], v[194:195] op_sel_hi:[1,0]
	v_pk_mul_f32 v[78:79], v[78:79], v[194:195] op_sel_hi:[1,0]
	v_pk_mul_f32 v[68:69], v[68:69], v[194:195] op_sel_hi:[1,0]
	v_pk_mul_f32 v[70:71], v[70:71], v[194:195] op_sel_hi:[1,0]
	v_pk_mul_f32 v[180:181], v[72:73], s[0:1] op_sel_hi:[1,0]
	v_pk_mul_f32 v[182:183], v[74:75], s[0:1] op_sel_hi:[1,0]
	v_pk_mul_f32 v[184:185], v[64:65], s[0:1] op_sel_hi:[1,0]
	v_pk_mul_f32 v[186:187], v[66:67], s[0:1] op_sel_hi:[1,0]
	v_exp_f32_e32 v180, v180
	v_exp_f32_e32 v181, v181
	v_exp_f32_e32 v182, v182
	v_exp_f32_e32 v183, v183
	v_exp_f32_e32 v184, v184
	v_exp_f32_e32 v185, v185
	v_exp_f32_e32 v186, v186
	v_exp_f32_e32 v187, v187
	v_pk_add_f32 v[180:181], v[180:181], 1.0 op_sel_hi:[1,0]
	v_pk_add_f32 v[182:183], v[182:183], 1.0 op_sel_hi:[1,0]
	v_pk_add_f32 v[184:185], v[184:185], 1.0 op_sel_hi:[1,0]
	v_pk_add_f32 v[186:187], v[186:187], 1.0 op_sel_hi:[1,0]
	v_rcp_f32_e32 v180, v180
	v_rcp_f32_e32 v181, v181
	v_rcp_f32_e32 v182, v182
	v_rcp_f32_e32 v183, v183
	v_rcp_f32_e32 v184, v184
	v_rcp_f32_e32 v185, v185
	v_rcp_f32_e32 v186, v186
	v_rcp_f32_e32 v187, v187
	v_pk_mul_f32 v[180:181], v[72:73], v[180:181]
	v_pk_mul_f32 v[182:183], v[74:75], v[182:183]
	v_pk_mul_f32 v[184:185], v[64:65], v[184:185]
	v_pk_mul_f32 v[186:187], v[66:67], v[186:187]
	v_pk_mul_f32 v[76:77], v[76:77], v[180:181]
	v_pk_mul_f32 v[78:79], v[78:79], v[182:183]
	v_pk_mul_f32 v[68:69], v[68:69], v[184:185]
	v_pk_mul_f32 v[70:71], v[70:71], v[186:187]
	v_cvt_pk_bf16_f32 v72, v76, v77
	v_cvt_pk_bf16_f32 v73, v78, v79
	v_cvt_pk_bf16_f32 v74, v68, v69
	v_cvt_pk_bf16_f32 v75, v70, v71
	global_store_dwordx4 v[162:163], v[72:75], off nt
	v_pk_mul_f32 v[56:57], v[56:57], v[196:197] op_sel_hi:[1,0]
	v_pk_mul_f32 v[58:59], v[58:59], v[196:197] op_sel_hi:[1,0]
	v_pk_mul_f32 v[48:49], v[48:49], v[196:197] op_sel_hi:[1,0]
	v_pk_mul_f32 v[50:51], v[50:51], v[196:197] op_sel_hi:[1,0]
	v_pk_mul_f32 v[60:61], v[60:61], v[196:197] op_sel_hi:[1,0]
	v_pk_mul_f32 v[62:63], v[62:63], v[196:197] op_sel_hi:[1,0]
	v_pk_mul_f32 v[52:53], v[52:53], v[196:197] op_sel_hi:[1,0]
	v_pk_mul_f32 v[54:55], v[54:55], v[196:197] op_sel_hi:[1,0]
	v_pk_mul_f32 v[172:173], v[56:57], s[0:1] op_sel_hi:[1,0]
	v_pk_mul_f32 v[174:175], v[58:59], s[0:1] op_sel_hi:[1,0]
	v_pk_mul_f32 v[176:177], v[48:49], s[0:1] op_sel_hi:[1,0]
	v_pk_mul_f32 v[178:179], v[50:51], s[0:1] op_sel_hi:[1,0]
	v_exp_f32_e32 v172, v172
	v_exp_f32_e32 v173, v173
	v_exp_f32_e32 v174, v174
	v_exp_f32_e32 v175, v175
	v_exp_f32_e32 v176, v176
	v_exp_f32_e32 v177, v177
	v_exp_f32_e32 v178, v178
	v_exp_f32_e32 v179, v179
	v_pk_add_f32 v[172:173], v[172:173], 1.0 op_sel_hi:[1,0]
	v_pk_add_f32 v[174:175], v[174:175], 1.0 op_sel_hi:[1,0]
	v_pk_add_f32 v[176:177], v[176:177], 1.0 op_sel_hi:[1,0]
	v_pk_add_f32 v[178:179], v[178:179], 1.0 op_sel_hi:[1,0]
	v_rcp_f32_e32 v172, v172
	v_rcp_f32_e32 v173, v173
	v_rcp_f32_e32 v174, v174
	v_rcp_f32_e32 v175, v175
	v_rcp_f32_e32 v176, v176
	v_rcp_f32_e32 v177, v177
	v_rcp_f32_e32 v178, v178
	v_rcp_f32_e32 v179, v179
	v_pk_mul_f32 v[172:173], v[56:57], v[172:173]
	v_pk_mul_f32 v[174:175], v[58:59], v[174:175]
	v_pk_mul_f32 v[176:177], v[48:49], v[176:177]
	v_pk_mul_f32 v[178:179], v[50:51], v[178:179]
	v_pk_mul_f32 v[60:61], v[60:61], v[172:173]
	v_pk_mul_f32 v[62:63], v[62:63], v[174:175]
	v_pk_mul_f32 v[52:53], v[52:53], v[176:177]
	v_pk_mul_f32 v[54:55], v[54:55], v[178:179]
	v_cvt_pk_bf16_f32 v56, v60, v61
	v_cvt_pk_bf16_f32 v57, v62, v63
	v_cvt_pk_bf16_f32 v58, v52, v53
	v_cvt_pk_bf16_f32 v59, v54, v55
	global_store_dwordx4 v[164:165], v[56:59], off nt
	v_pk_mul_f32 v[40:41], v[40:41], v[198:199] op_sel_hi:[1,0]
	v_pk_mul_f32 v[42:43], v[42:43], v[198:199] op_sel_hi:[1,0]
	v_pk_mul_f32 v[32:33], v[32:33], v[198:199] op_sel_hi:[1,0]
	v_pk_mul_f32 v[34:35], v[34:35], v[198:199] op_sel_hi:[1,0]
	v_pk_mul_f32 v[44:45], v[44:45], v[198:199] op_sel_hi:[1,0]
	v_pk_mul_f32 v[46:47], v[46:47], v[198:199] op_sel_hi:[1,0]
	v_pk_mul_f32 v[36:37], v[36:37], v[198:199] op_sel_hi:[1,0]
	v_pk_mul_f32 v[38:39], v[38:39], v[198:199] op_sel_hi:[1,0]
	v_pk_mul_f32 v[180:181], v[40:41], s[0:1] op_sel_hi:[1,0]
	v_pk_mul_f32 v[182:183], v[42:43], s[0:1] op_sel_hi:[1,0]
	v_pk_mul_f32 v[184:185], v[32:33], s[0:1] op_sel_hi:[1,0]
	v_pk_mul_f32 v[186:187], v[34:35], s[0:1] op_sel_hi:[1,0]
	v_exp_f32_e32 v180, v180
	v_exp_f32_e32 v181, v181
	v_exp_f32_e32 v182, v182
	v_exp_f32_e32 v183, v183
	v_exp_f32_e32 v184, v184
	v_exp_f32_e32 v185, v185
	v_exp_f32_e32 v186, v186
	v_exp_f32_e32 v187, v187
	v_pk_add_f32 v[180:181], v[180:181], 1.0 op_sel_hi:[1,0]
	v_pk_add_f32 v[182:183], v[182:183], 1.0 op_sel_hi:[1,0]
	v_pk_add_f32 v[184:185], v[184:185], 1.0 op_sel_hi:[1,0]
	v_pk_add_f32 v[186:187], v[186:187], 1.0 op_sel_hi:[1,0]
	v_rcp_f32_e32 v180, v180
	v_rcp_f32_e32 v181, v181
	v_rcp_f32_e32 v182, v182
	v_rcp_f32_e32 v183, v183
	v_rcp_f32_e32 v184, v184
	v_rcp_f32_e32 v185, v185
	v_rcp_f32_e32 v186, v186
	v_rcp_f32_e32 v187, v187
	v_pk_mul_f32 v[180:181], v[40:41], v[180:181]
	v_pk_mul_f32 v[182:183], v[42:43], v[182:183]
	v_pk_mul_f32 v[184:185], v[32:33], v[184:185]
	v_pk_mul_f32 v[186:187], v[34:35], v[186:187]
	v_pk_mul_f32 v[44:45], v[44:45], v[180:181]
	v_pk_mul_f32 v[46:47], v[46:47], v[182:183]
	v_pk_mul_f32 v[36:37], v[36:37], v[184:185]
	v_pk_mul_f32 v[38:39], v[38:39], v[186:187]
	v_cvt_pk_bf16_f32 v40, v44, v45
	v_cvt_pk_bf16_f32 v41, v46, v47
	v_cvt_pk_bf16_f32 v42, v36, v37
	v_cvt_pk_bf16_f32 v43, v38, v39
	global_store_dwordx4 v[166:167], v[40:43], off nt
	v_pk_mul_f32 v[24:25], v[24:25], v[200:201] op_sel_hi:[1,0]
	v_pk_mul_f32 v[26:27], v[26:27], v[200:201] op_sel_hi:[1,0]
	v_pk_mul_f32 v[16:17], v[16:17], v[200:201] op_sel_hi:[1,0]
	v_pk_mul_f32 v[18:19], v[18:19], v[200:201] op_sel_hi:[1,0]
	v_pk_mul_f32 v[28:29], v[28:29], v[200:201] op_sel_hi:[1,0]
	v_pk_mul_f32 v[30:31], v[30:31], v[200:201] op_sel_hi:[1,0]
	v_pk_mul_f32 v[20:21], v[20:21], v[200:201] op_sel_hi:[1,0]
	v_pk_mul_f32 v[22:23], v[22:23], v[200:201] op_sel_hi:[1,0]
	v_pk_mul_f32 v[172:173], v[24:25], s[0:1] op_sel_hi:[1,0]
	v_pk_mul_f32 v[174:175], v[26:27], s[0:1] op_sel_hi:[1,0]
	v_pk_mul_f32 v[176:177], v[16:17], s[0:1] op_sel_hi:[1,0]
	v_pk_mul_f32 v[178:179], v[18:19], s[0:1] op_sel_hi:[1,0]
	v_exp_f32_e32 v172, v172
	v_exp_f32_e32 v173, v173
	v_exp_f32_e32 v174, v174
	v_exp_f32_e32 v175, v175
	v_exp_f32_e32 v176, v176
	v_exp_f32_e32 v177, v177
	v_exp_f32_e32 v178, v178
	v_exp_f32_e32 v179, v179
	v_pk_add_f32 v[172:173], v[172:173], 1.0 op_sel_hi:[1,0]
	v_pk_add_f32 v[174:175], v[174:175], 1.0 op_sel_hi:[1,0]
	v_pk_add_f32 v[176:177], v[176:177], 1.0 op_sel_hi:[1,0]
	v_pk_add_f32 v[178:179], v[178:179], 1.0 op_sel_hi:[1,0]
	v_rcp_f32_e32 v172, v172
	v_rcp_f32_e32 v173, v173
	v_rcp_f32_e32 v174, v174
	v_rcp_f32_e32 v175, v175
	v_rcp_f32_e32 v176, v176
	v_rcp_f32_e32 v177, v177
	v_rcp_f32_e32 v178, v178
	v_rcp_f32_e32 v179, v179
	v_pk_mul_f32 v[172:173], v[24:25], v[172:173]
	v_pk_mul_f32 v[174:175], v[26:27], v[174:175]
	v_pk_mul_f32 v[176:177], v[16:17], v[176:177]
	v_pk_mul_f32 v[178:179], v[18:19], v[178:179]
	v_pk_mul_f32 v[28:29], v[28:29], v[172:173]
	v_pk_mul_f32 v[30:31], v[30:31], v[174:175]
	v_pk_mul_f32 v[20:21], v[20:21], v[176:177]
	v_pk_mul_f32 v[22:23], v[22:23], v[178:179]
	v_cvt_pk_bf16_f32 v24, v28, v29
	v_cvt_pk_bf16_f32 v25, v30, v31
	v_cvt_pk_bf16_f32 v26, v20, v21
	v_cvt_pk_bf16_f32 v27, v22, v23
	global_store_dwordx4 v[168:169], v[24:27], off nt
	v_pk_mul_f32 v[8:9], v[8:9], v[202:203] op_sel_hi:[1,0]
	v_pk_mul_f32 v[10:11], v[10:11], v[202:203] op_sel_hi:[1,0]
	v_pk_mul_f32 v[0:1], v[0:1], v[202:203] op_sel_hi:[1,0]
	v_pk_mul_f32 v[2:3], v[2:3], v[202:203] op_sel_hi:[1,0]
	v_pk_mul_f32 v[12:13], v[12:13], v[202:203] op_sel_hi:[1,0]
	v_pk_mul_f32 v[14:15], v[14:15], v[202:203] op_sel_hi:[1,0]
	v_pk_mul_f32 v[4:5], v[4:5], v[202:203] op_sel_hi:[1,0]
	v_pk_mul_f32 v[6:7], v[6:7], v[202:203] op_sel_hi:[1,0]
	v_pk_mul_f32 v[180:181], v[8:9], s[0:1] op_sel_hi:[1,0]
	v_pk_mul_f32 v[182:183], v[10:11], s[0:1] op_sel_hi:[1,0]
	v_pk_mul_f32 v[184:185], v[0:1], s[0:1] op_sel_hi:[1,0]
	v_pk_mul_f32 v[186:187], v[2:3], s[0:1] op_sel_hi:[1,0]
	v_exp_f32_e32 v180, v180
	v_exp_f32_e32 v181, v181
	v_exp_f32_e32 v182, v182
	v_exp_f32_e32 v183, v183
	v_exp_f32_e32 v184, v184
	v_exp_f32_e32 v185, v185
	v_exp_f32_e32 v186, v186
	v_exp_f32_e32 v187, v187
	v_pk_add_f32 v[180:181], v[180:181], 1.0 op_sel_hi:[1,0]
	v_pk_add_f32 v[182:183], v[182:183], 1.0 op_sel_hi:[1,0]
	v_pk_add_f32 v[184:185], v[184:185], 1.0 op_sel_hi:[1,0]
	v_pk_add_f32 v[186:187], v[186:187], 1.0 op_sel_hi:[1,0]
	v_rcp_f32_e32 v180, v180
	v_rcp_f32_e32 v181, v181
	v_rcp_f32_e32 v182, v182
	v_rcp_f32_e32 v183, v183
	v_rcp_f32_e32 v184, v184
	v_rcp_f32_e32 v185, v185
	v_rcp_f32_e32 v186, v186
	v_rcp_f32_e32 v187, v187
	v_pk_mul_f32 v[180:181], v[8:9], v[180:181]
	v_pk_mul_f32 v[182:183], v[10:11], v[182:183]
	v_pk_mul_f32 v[184:185], v[0:1], v[184:185]
	v_pk_mul_f32 v[186:187], v[2:3], v[186:187]
	v_pk_mul_f32 v[12:13], v[12:13], v[180:181]
	v_pk_mul_f32 v[14:15], v[14:15], v[182:183]
	v_pk_mul_f32 v[4:5], v[4:5], v[184:185]
	v_pk_mul_f32 v[6:7], v[6:7], v[186:187]
	v_cvt_pk_bf16_f32 v8, v12, v13
	v_cvt_pk_bf16_f32 v9, v14, v15
	v_cvt_pk_bf16_f32 v10, v4, v5
	v_cvt_pk_bf16_f32 v11, v6, v7
	global_store_dwordx4 v[170:171], v[8:11], off nt
	s_andn2_b64 vcc, exec, s[4:5]
	s_mov_b64 s[0:1], -1
	s_cbranch_vccnz .LBB0_1045
	s_andn2_b64 vcc, exec, s[8:9]
	s_cbranch_vccnz .LBB0_1044
	s_barrier
	s_branch .LBB0_1044
